# prologue adaLN GEMV: the 16 serialized nontemporal weight loads of each unrolled block issued together with counted waits
# speedup vs baseline: 1.0185x; 1.0052x over previous
.LBB0_29:
	v_add_u32_e32 v39, s8, v35
	v_mad_i64_i32 v[128:129], s[12:13], v39, s86, v[28:29]
	global_load_dwordx4 v[64:67], v[128:129], off nt
	v_add_u32_e32 v130, 2, v39
	v_mad_i64_i32 v[128:129], s[12:13], v130, s86, v[28:29]
	global_load_dwordx4 v[68:71], v[128:129], off nt
	v_add_u32_e32 v130, 4, v39
	v_mad_i64_i32 v[128:129], s[12:13], v130, s86, v[28:29]
	global_load_dwordx4 v[72:75], v[128:129], off nt
	v_add_u32_e32 v130, 6, v39
	v_mad_i64_i32 v[128:129], s[12:13], v130, s86, v[28:29]
	global_load_dwordx4 v[76:79], v[128:129], off nt
	v_add_u32_e32 v130, 8, v39
	v_mad_i64_i32 v[128:129], s[12:13], v130, s86, v[28:29]
	global_load_dwordx4 v[80:83], v[128:129], off nt
	v_add_u32_e32 v130, 10, v39
	v_mad_i64_i32 v[128:129], s[12:13], v130, s86, v[28:29]
	global_load_dwordx4 v[84:87], v[128:129], off nt
	v_add_u32_e32 v130, 12, v39
	v_mad_i64_i32 v[128:129], s[12:13], v130, s86, v[28:29]
	global_load_dwordx4 v[88:91], v[128:129], off nt
	v_add_u32_e32 v130, 14, v39
	v_mad_i64_i32 v[128:129], s[12:13], v130, s86, v[28:29]
	global_load_dwordx4 v[92:95], v[128:129], off nt
	v_add_u32_e32 v130, 16, v39
	v_mad_i64_i32 v[128:129], s[12:13], v130, s86, v[28:29]
	global_load_dwordx4 v[96:99], v[128:129], off nt
	v_add_u32_e32 v130, 18, v39
	v_mad_i64_i32 v[128:129], s[12:13], v130, s86, v[28:29]
	global_load_dwordx4 v[100:103], v[128:129], off nt
	v_add_u32_e32 v130, 20, v39
	v_mad_i64_i32 v[128:129], s[12:13], v130, s86, v[28:29]
	global_load_dwordx4 v[104:107], v[128:129], off nt
	v_add_u32_e32 v130, 22, v39
	v_mad_i64_i32 v[128:129], s[12:13], v130, s86, v[28:29]
	global_load_dwordx4 v[108:111], v[128:129], off nt
	v_add_u32_e32 v130, 24, v39
	v_mad_i64_i32 v[128:129], s[12:13], v130, s86, v[28:29]
	global_load_dwordx4 v[112:115], v[128:129], off nt
	v_add_u32_e32 v130, 26, v39
	v_mad_i64_i32 v[128:129], s[12:13], v130, s86, v[28:29]
	global_load_dwordx4 v[116:119], v[128:129], off nt
	v_add_u32_e32 v130, 28, v39
	v_mad_i64_i32 v[128:129], s[12:13], v130, s86, v[28:29]
	global_load_dwordx4 v[120:123], v[128:129], off nt
	v_add_u32_e32 v130, 30, v39
	v_mad_i64_i32 v[128:129], s[12:13], v130, s86, v[28:29]
	global_load_dwordx4 v[124:127], v[128:129], off nt
	v_add_u32_e32 v40, 0x1000, v38
	v_add_u32_e32 v41, 0x2000, v38
	v_add_u32_e32 v42, 0x3000, v38
	v_add_u32_e32 v43, 0x4000, v38
	ds_read2_b32 v[44:45], v38 offset1:2
	ds_read2_b32 v[46:47], v38 offset0:4 offset1:6
	ds_read2_b32 v[48:49], v38 offset0:8 offset1:10
	ds_read2_b32 v[50:51], v38 offset0:12 offset1:14
	ds_read2_b32 v[52:53], v40 offset1:2
	ds_read2_b32 v[54:55], v41 offset1:2
	ds_read2_b32 v[56:57], v42 offset1:2
	ds_read2_b32 v[58:59], v43 offset1:2
	s_add_i32 s8, s8, 32
	s_cmpk_lg_i32 s8, 0x80
	s_waitcnt vmcnt(15) lgkmcnt(7)
	v_pk_fma_f32 v[18:19], v[64:65], v[44:45], v[18:19] op_sel_hi:[1,0,1]
	s_waitcnt lgkmcnt(3)
	v_pk_fma_f32 v[14:15], v[64:65], v[52:53], v[14:15] op_sel_hi:[1,0,1]
	s_waitcnt lgkmcnt(2)
	v_pk_fma_f32 v[10:11], v[64:65], v[54:55], v[10:11] op_sel_hi:[1,0,1]
	s_waitcnt lgkmcnt(1)
	v_pk_fma_f32 v[6:7], v[64:65], v[56:57], v[6:7] op_sel_hi:[1,0,1]
	s_waitcnt lgkmcnt(0)
	v_pk_fma_f32 v[30:31], v[64:65], v[58:59], v[2:3] op_sel_hi:[1,0,1]
	v_pk_fma_f32 v[20:21], v[66:67], v[44:45], v[20:21] op_sel_hi:[1,0,1]
	v_pk_fma_f32 v[16:17], v[66:67], v[52:53], v[16:17] op_sel_hi:[1,0,1]
	v_pk_fma_f32 v[12:13], v[66:67], v[54:55], v[12:13] op_sel_hi:[1,0,1]
	v_pk_fma_f32 v[8:9], v[66:67], v[56:57], v[8:9] op_sel_hi:[1,0,1]
	v_pk_fma_f32 v[32:33], v[66:67], v[58:59], v[4:5] op_sel_hi:[1,0,1]
	v_mov_b32_e32 v44, v45
	s_waitcnt vmcnt(14)
	v_pk_fma_f32 v[20:21], v[70:71], v[44:45], v[20:21] op_sel_hi:[1,0,1]
	v_pk_fma_f32 v[18:19], v[68:69], v[44:45], v[18:19] op_sel_hi:[1,0,1]
	v_mov_b32_e32 v44, v53
	v_pk_fma_f32 v[16:17], v[70:71], v[44:45], v[16:17] op_sel_hi:[1,0,1]
	v_pk_fma_f32 v[14:15], v[68:69], v[44:45], v[14:15] op_sel_hi:[1,0,1]
	v_mov_b32_e32 v44, v55
	v_pk_fma_f32 v[12:13], v[70:71], v[44:45], v[12:13] op_sel_hi:[1,0,1]
	v_pk_fma_f32 v[10:11], v[68:69], v[44:45], v[10:11] op_sel_hi:[1,0,1]
	v_mov_b32_e32 v44, v57
	v_pk_fma_f32 v[8:9], v[70:71], v[44:45], v[8:9] op_sel_hi:[1,0,1]
	v_pk_fma_f32 v[6:7], v[68:69], v[44:45], v[6:7] op_sel_hi:[1,0,1]
	v_mov_b32_e32 v44, v59
	v_pk_fma_f32 v[30:31], v[68:69], v[44:45], v[30:31] op_sel_hi:[1,0,1]
	v_pk_fma_f32 v[32:33], v[70:71], v[44:45], v[32:33] op_sel_hi:[1,0,1]
	ds_read2_b32 v[44:45], v40 offset0:4 offset1:6
	ds_read2_b32 v[52:53], v41 offset0:4 offset1:6
	ds_read2_b32 v[54:55], v42 offset0:4 offset1:6
	ds_read2_b32 v[56:57], v43 offset0:4 offset1:6
	ds_read2_b32 v[58:59], v43 offset0:12 offset1:14
	s_waitcnt vmcnt(13)
	v_pk_fma_f32 v[18:19], v[72:73], v[46:47], v[18:19] op_sel_hi:[1,0,1]
	s_waitcnt lgkmcnt(4)
	v_pk_fma_f32 v[14:15], v[72:73], v[44:45], v[14:15] op_sel_hi:[1,0,1]
	s_waitcnt lgkmcnt(3)
	v_pk_fma_f32 v[10:11], v[72:73], v[52:53], v[10:11] op_sel_hi:[1,0,1]
	s_waitcnt lgkmcnt(2)
	v_pk_fma_f32 v[6:7], v[72:73], v[54:55], v[6:7] op_sel_hi:[1,0,1]
	s_waitcnt lgkmcnt(1)
	v_pk_fma_f32 v[30:31], v[72:73], v[56:57], v[30:31] op_sel_hi:[1,0,1]
	v_pk_fma_f32 v[20:21], v[74:75], v[46:47], v[20:21] op_sel_hi:[1,0,1]
	v_pk_fma_f32 v[16:17], v[74:75], v[44:45], v[16:17] op_sel_hi:[1,0,1]
	v_pk_fma_f32 v[12:13], v[74:75], v[52:53], v[12:13] op_sel_hi:[1,0,1]
	v_pk_fma_f32 v[8:9], v[74:75], v[54:55], v[8:9] op_sel_hi:[1,0,1]
	v_pk_fma_f32 v[32:33], v[74:75], v[56:57], v[32:33] op_sel_hi:[1,0,1]
	v_mov_b32_e32 v44, v47
	ds_read2_b32 v[46:47], v41 offset0:8 offset1:10
	s_waitcnt vmcnt(12)
	v_pk_fma_f32 v[20:21], v[78:79], v[44:45], v[20:21] op_sel_hi:[1,0,1]
	v_pk_fma_f32 v[18:19], v[76:77], v[44:45], v[18:19] op_sel_hi:[1,0,1]
	v_mov_b32_e32 v44, v45
	v_pk_fma_f32 v[16:17], v[78:79], v[44:45], v[16:17] op_sel_hi:[1,0,1]
	v_pk_fma_f32 v[14:15], v[76:77], v[44:45], v[14:15] op_sel_hi:[1,0,1]
	v_mov_b32_e32 v44, v53
	v_pk_fma_f32 v[12:13], v[78:79], v[44:45], v[12:13] op_sel_hi:[1,0,1]
	v_pk_fma_f32 v[10:11], v[76:77], v[44:45], v[10:11] op_sel_hi:[1,0,1]
	v_mov_b32_e32 v44, v55
	v_pk_fma_f32 v[8:9], v[78:79], v[44:45], v[8:9] op_sel_hi:[1,0,1]
	v_pk_fma_f32 v[6:7], v[76:77], v[44:45], v[6:7] op_sel_hi:[1,0,1]
	v_mov_b32_e32 v44, v57
	v_pk_fma_f32 v[30:31], v[76:77], v[44:45], v[30:31] op_sel_hi:[1,0,1]
	v_pk_fma_f32 v[32:33], v[78:79], v[44:45], v[32:33] op_sel_hi:[1,0,1]
	ds_read2_b32 v[44:45], v40 offset0:8 offset1:10
	ds_read2_b32 v[52:53], v42 offset0:8 offset1:10
	ds_read2_b32 v[54:55], v43 offset0:8 offset1:10
	s_waitcnt vmcnt(11)
	v_pk_fma_f32 v[18:19], v[80:81], v[48:49], v[18:19] op_sel_hi:[1,0,1]
	s_waitcnt lgkmcnt(2)
	v_pk_fma_f32 v[14:15], v[80:81], v[44:45], v[14:15] op_sel_hi:[1,0,1]
	v_pk_fma_f32 v[10:11], v[80:81], v[46:47], v[10:11] op_sel_hi:[1,0,1]
	s_waitcnt lgkmcnt(1)
	v_pk_fma_f32 v[6:7], v[80:81], v[52:53], v[6:7] op_sel_hi:[1,0,1]
	s_waitcnt lgkmcnt(0)
	v_pk_fma_f32 v[30:31], v[80:81], v[54:55], v[30:31] op_sel_hi:[1,0,1]
	v_pk_fma_f32 v[20:21], v[82:83], v[48:49], v[20:21] op_sel_hi:[1,0,1]
	v_pk_fma_f32 v[16:17], v[82:83], v[44:45], v[16:17] op_sel_hi:[1,0,1]
	v_pk_fma_f32 v[12:13], v[82:83], v[46:47], v[12:13] op_sel_hi:[1,0,1]
	v_pk_fma_f32 v[8:9], v[82:83], v[52:53], v[8:9] op_sel_hi:[1,0,1]
	v_pk_fma_f32 v[32:33], v[82:83], v[54:55], v[32:33] op_sel_hi:[1,0,1]
	v_mov_b32_e32 v44, v49
	ds_read2_b32 v[48:49], v41 offset0:12 offset1:14
	s_waitcnt vmcnt(10)
	v_pk_fma_f32 v[20:21], v[86:87], v[44:45], v[20:21] op_sel_hi:[1,0,1]
	v_pk_fma_f32 v[18:19], v[84:85], v[44:45], v[18:19] op_sel_hi:[1,0,1]
	v_mov_b32_e32 v44, v45
	v_pk_fma_f32 v[16:17], v[86:87], v[44:45], v[16:17] op_sel_hi:[1,0,1]
	v_pk_fma_f32 v[14:15], v[84:85], v[44:45], v[14:15] op_sel_hi:[1,0,1]
	v_mov_b32_e32 v44, v47
	v_pk_fma_f32 v[12:13], v[86:87], v[44:45], v[12:13] op_sel_hi:[1,0,1]
	v_pk_fma_f32 v[10:11], v[84:85], v[44:45], v[10:11] op_sel_hi:[1,0,1]
	v_mov_b32_e32 v44, v53
	v_pk_fma_f32 v[8:9], v[86:87], v[44:45], v[8:9] op_sel_hi:[1,0,1]
	v_pk_fma_f32 v[6:7], v[84:85], v[44:45], v[6:7] op_sel_hi:[1,0,1]
	v_mov_b32_e32 v44, v55
	v_pk_fma_f32 v[30:31], v[84:85], v[44:45], v[30:31] op_sel_hi:[1,0,1]
	v_pk_fma_f32 v[32:33], v[86:87], v[44:45], v[32:33] op_sel_hi:[1,0,1]
	ds_read2_b32 v[44:45], v40 offset0:12 offset1:14
	s_waitcnt vmcnt(9) lgkmcnt(1)
	v_pk_fma_f32 v[52:53], v[88:89], v[48:49], v[10:11] op_sel_hi:[1,0,1]
	v_pk_fma_f32 v[10:11], v[90:91], v[48:49], v[12:13] op_sel_hi:[1,0,1]
	ds_read2_b32 v[12:13], v42 offset0:12 offset1:14
	v_pk_fma_f32 v[18:19], v[88:89], v[50:51], v[18:19] op_sel_hi:[1,0,1]
	s_waitcnt lgkmcnt(1)
	v_pk_fma_f32 v[14:15], v[88:89], v[44:45], v[14:15] op_sel_hi:[1,0,1]
	v_pk_fma_f32 v[60:61], v[88:89], v[58:59], v[30:31] op_sel_hi:[1,0,1]
	v_pk_fma_f32 v[20:21], v[90:91], v[50:51], v[20:21] op_sel_hi:[1,0,1]
	s_waitcnt lgkmcnt(0)
	v_pk_fma_f32 v[54:55], v[88:89], v[12:13], v[6:7] op_sel_hi:[1,0,1]
	v_pk_fma_f32 v[46:47], v[90:91], v[44:45], v[16:17] op_sel_hi:[1,0,1]
	v_pk_fma_f32 v[56:57], v[90:91], v[12:13], v[8:9] op_sel_hi:[1,0,1]
	v_pk_fma_f32 v[32:33], v[90:91], v[58:59], v[32:33] op_sel_hi:[1,0,1]
	v_mov_b32_e32 v8, v51
	v_mov_b32_e32 v12, v45
	v_mov_b32_e32 v44, v59
	ds_read2_b32 v[50:51], v42 offset0:16 offset1:18
	s_waitcnt vmcnt(8)
	v_pk_fma_f32 v[6:7], v[94:95], v[8:9], v[20:21] op_sel_hi:[1,0,1]
	v_pk_fma_f32 v[16:17], v[92:93], v[8:9], v[18:19] op_sel_hi:[1,0,1]
	v_pk_fma_f32 v[8:9], v[94:95], v[12:13], v[46:47] op_sel_hi:[1,0,1]
	v_pk_fma_f32 v[18:19], v[92:93], v[12:13], v[14:15] op_sel_hi:[1,0,1]
	v_mov_b32_e32 v12, v49
	v_mov_b32_e32 v14, v13
	v_pk_fma_f32 v[10:11], v[94:95], v[12:13], v[10:11] op_sel_hi:[1,0,1]
	v_pk_fma_f32 v[20:21], v[92:93], v[12:13], v[52:53] op_sel_hi:[1,0,1]
	v_pk_fma_f32 v[12:13], v[94:95], v[14:15], v[56:57] op_sel_hi:[1,0,1]
	v_pk_fma_f32 v[30:31], v[92:93], v[14:15], v[54:55] op_sel_hi:[1,0,1]
	v_pk_fma_f32 v[14:15], v[94:95], v[44:45], v[32:33] op_sel_hi:[1,0,1]
	v_pk_fma_f32 v[32:33], v[92:93], v[44:45], v[60:61] op_sel_hi:[1,0,1]
	ds_read2_b32 v[44:45], v38 offset0:16 offset1:18
	ds_read2_b32 v[46:47], v40 offset0:16 offset1:18
	ds_read2_b32 v[48:49], v41 offset0:16 offset1:18
	ds_read2_b32 v[52:53], v43 offset0:16 offset1:18
	s_waitcnt vmcnt(7) lgkmcnt(3)
	v_pk_fma_f32 v[16:17], v[96:97], v[44:45], v[16:17] op_sel_hi:[1,0,1]
	s_waitcnt lgkmcnt(2)
	v_pk_fma_f32 v[18:19], v[96:97], v[46:47], v[18:19] op_sel_hi:[1,0,1]
	s_waitcnt lgkmcnt(1)
	v_pk_fma_f32 v[20:21], v[96:97], v[48:49], v[20:21] op_sel_hi:[1,0,1]
	v_pk_fma_f32 v[30:31], v[96:97], v[50:51], v[30:31] op_sel_hi:[1,0,1]
	s_waitcnt lgkmcnt(0)
	v_pk_fma_f32 v[32:33], v[96:97], v[52:53], v[32:33] op_sel_hi:[1,0,1]
	v_pk_fma_f32 v[6:7], v[98:99], v[44:45], v[6:7] op_sel_hi:[1,0,1]
	v_pk_fma_f32 v[8:9], v[98:99], v[46:47], v[8:9] op_sel_hi:[1,0,1]
	v_pk_fma_f32 v[10:11], v[98:99], v[48:49], v[10:11] op_sel_hi:[1,0,1]
	v_pk_fma_f32 v[12:13], v[98:99], v[50:51], v[12:13] op_sel_hi:[1,0,1]
	v_pk_fma_f32 v[14:15], v[98:99], v[52:53], v[14:15] op_sel_hi:[1,0,1]
	v_mov_b32_e32 v44, v45
	s_waitcnt vmcnt(6)
	v_pk_fma_f32 v[6:7], v[102:103], v[44:45], v[6:7] op_sel_hi:[1,0,1]
	v_pk_fma_f32 v[16:17], v[100:101], v[44:45], v[16:17] op_sel_hi:[1,0,1]
	v_mov_b32_e32 v44, v47
	v_pk_fma_f32 v[8:9], v[102:103], v[44:45], v[8:9] op_sel_hi:[1,0,1]
	v_pk_fma_f32 v[18:19], v[100:101], v[44:45], v[18:19] op_sel_hi:[1,0,1]
	v_mov_b32_e32 v44, v49
	v_pk_fma_f32 v[10:11], v[102:103], v[44:45], v[10:11] op_sel_hi:[1,0,1]
	v_pk_fma_f32 v[20:21], v[100:101], v[44:45], v[20:21] op_sel_hi:[1,0,1]
	v_mov_b32_e32 v44, v51
	v_pk_fma_f32 v[12:13], v[102:103], v[44:45], v[12:13] op_sel_hi:[1,0,1]
	v_pk_fma_f32 v[30:31], v[100:101], v[44:45], v[30:31] op_sel_hi:[1,0,1]
	v_mov_b32_e32 v44, v53
	v_pk_fma_f32 v[32:33], v[100:101], v[44:45], v[32:33] op_sel_hi:[1,0,1]
	v_pk_fma_f32 v[14:15], v[102:103], v[44:45], v[14:15] op_sel_hi:[1,0,1]
	ds_read2_b32 v[44:45], v38 offset0:20 offset1:22
	ds_read2_b32 v[46:47], v40 offset0:20 offset1:22
	ds_read2_b32 v[48:49], v41 offset0:20 offset1:22
	ds_read2_b32 v[50:51], v42 offset0:20 offset1:22
	ds_read2_b32 v[52:53], v43 offset0:20 offset1:22
	s_waitcnt vmcnt(5) lgkmcnt(4)
	v_pk_fma_f32 v[16:17], v[104:105], v[44:45], v[16:17] op_sel_hi:[1,0,1]
	s_waitcnt lgkmcnt(3)
	v_pk_fma_f32 v[18:19], v[104:105], v[46:47], v[18:19] op_sel_hi:[1,0,1]
	s_waitcnt lgkmcnt(2)
	v_pk_fma_f32 v[20:21], v[104:105], v[48:49], v[20:21] op_sel_hi:[1,0,1]
	s_waitcnt lgkmcnt(1)
	v_pk_fma_f32 v[30:31], v[104:105], v[50:51], v[30:31] op_sel_hi:[1,0,1]
	s_waitcnt lgkmcnt(0)
	v_pk_fma_f32 v[32:33], v[104:105], v[52:53], v[32:33] op_sel_hi:[1,0,1]
	v_pk_fma_f32 v[6:7], v[106:107], v[44:45], v[6:7] op_sel_hi:[1,0,1]
	v_pk_fma_f32 v[8:9], v[106:107], v[46:47], v[8:9] op_sel_hi:[1,0,1]
	v_pk_fma_f32 v[10:11], v[106:107], v[48:49], v[10:11] op_sel_hi:[1,0,1]
	v_pk_fma_f32 v[12:13], v[106:107], v[50:51], v[12:13] op_sel_hi:[1,0,1]
	v_pk_fma_f32 v[14:15], v[106:107], v[52:53], v[14:15] op_sel_hi:[1,0,1]
	v_mov_b32_e32 v44, v45
	s_waitcnt vmcnt(4)
	v_pk_fma_f32 v[6:7], v[110:111], v[44:45], v[6:7] op_sel_hi:[1,0,1]
	v_pk_fma_f32 v[16:17], v[108:109], v[44:45], v[16:17] op_sel_hi:[1,0,1]
	v_mov_b32_e32 v44, v47
	v_pk_fma_f32 v[8:9], v[110:111], v[44:45], v[8:9] op_sel_hi:[1,0,1]
	v_pk_fma_f32 v[18:19], v[108:109], v[44:45], v[18:19] op_sel_hi:[1,0,1]
	v_mov_b32_e32 v44, v49
	v_pk_fma_f32 v[10:11], v[110:111], v[44:45], v[10:11] op_sel_hi:[1,0,1]
	v_pk_fma_f32 v[20:21], v[108:109], v[44:45], v[20:21] op_sel_hi:[1,0,1]
	v_mov_b32_e32 v44, v51
	v_pk_fma_f32 v[12:13], v[110:111], v[44:45], v[12:13] op_sel_hi:[1,0,1]
	v_pk_fma_f32 v[30:31], v[108:109], v[44:45], v[30:31] op_sel_hi:[1,0,1]
	v_mov_b32_e32 v44, v53
	v_pk_fma_f32 v[32:33], v[108:109], v[44:45], v[32:33] op_sel_hi:[1,0,1]
	v_pk_fma_f32 v[14:15], v[110:111], v[44:45], v[14:15] op_sel_hi:[1,0,1]
	ds_read2_b32 v[44:45], v38 offset0:24 offset1:26
	ds_read2_b32 v[46:47], v40 offset0:24 offset1:26
	ds_read2_b32 v[48:49], v41 offset0:24 offset1:26
	ds_read2_b32 v[50:51], v42 offset0:24 offset1:26
	ds_read2_b32 v[52:53], v43 offset0:24 offset1:26
	s_waitcnt vmcnt(3) lgkmcnt(4)
	v_pk_fma_f32 v[16:17], v[112:113], v[44:45], v[16:17] op_sel_hi:[1,0,1]
	s_waitcnt lgkmcnt(3)
	v_pk_fma_f32 v[18:19], v[112:113], v[46:47], v[18:19] op_sel_hi:[1,0,1]
	s_waitcnt lgkmcnt(2)
	v_pk_fma_f32 v[20:21], v[112:113], v[48:49], v[20:21] op_sel_hi:[1,0,1]
	s_waitcnt lgkmcnt(1)
	v_pk_fma_f32 v[30:31], v[112:113], v[50:51], v[30:31] op_sel_hi:[1,0,1]
	s_waitcnt lgkmcnt(0)
	v_pk_fma_f32 v[32:33], v[112:113], v[52:53], v[32:33] op_sel_hi:[1,0,1]
	v_pk_fma_f32 v[6:7], v[114:115], v[44:45], v[6:7] op_sel_hi:[1,0,1]
	v_pk_fma_f32 v[8:9], v[114:115], v[46:47], v[8:9] op_sel_hi:[1,0,1]
	v_pk_fma_f32 v[10:11], v[114:115], v[48:49], v[10:11] op_sel_hi:[1,0,1]
	v_pk_fma_f32 v[12:13], v[114:115], v[50:51], v[12:13] op_sel_hi:[1,0,1]
	v_pk_fma_f32 v[14:15], v[114:115], v[52:53], v[14:15] op_sel_hi:[1,0,1]
	v_mov_b32_e32 v44, v45
	s_waitcnt vmcnt(2)
	v_pk_fma_f32 v[6:7], v[118:119], v[44:45], v[6:7] op_sel_hi:[1,0,1]
	v_pk_fma_f32 v[16:17], v[116:117], v[44:45], v[16:17] op_sel_hi:[1,0,1]
	v_mov_b32_e32 v44, v47
	v_pk_fma_f32 v[8:9], v[118:119], v[44:45], v[8:9] op_sel_hi:[1,0,1]
	v_pk_fma_f32 v[18:19], v[116:117], v[44:45], v[18:19] op_sel_hi:[1,0,1]
	v_mov_b32_e32 v44, v49
	v_pk_fma_f32 v[10:11], v[118:119], v[44:45], v[10:11] op_sel_hi:[1,0,1]
	v_pk_fma_f32 v[20:21], v[116:117], v[44:45], v[20:21] op_sel_hi:[1,0,1]
	v_mov_b32_e32 v44, v51
	v_pk_fma_f32 v[12:13], v[118:119], v[44:45], v[12:13] op_sel_hi:[1,0,1]
	v_pk_fma_f32 v[30:31], v[116:117], v[44:45], v[30:31] op_sel_hi:[1,0,1]
	v_mov_b32_e32 v44, v53
	v_pk_fma_f32 v[32:33], v[116:117], v[44:45], v[32:33] op_sel_hi:[1,0,1]
	v_pk_fma_f32 v[14:15], v[118:119], v[44:45], v[14:15] op_sel_hi:[1,0,1]
	ds_read2_b32 v[44:45], v38 offset0:28 offset1:30
	ds_read2_b32 v[46:47], v40 offset0:28 offset1:30
	ds_read2_b32 v[40:41], v41 offset0:28 offset1:30
	ds_read2_b32 v[52:53], v42 offset0:28 offset1:30
	ds_read2_b32 v[42:43], v43 offset0:28 offset1:30
	v_add_u32_e32 v38, 0x80, v38
	s_waitcnt vmcnt(1) lgkmcnt(4)
	v_pk_fma_f32 v[16:17], v[120:121], v[44:45], v[16:17] op_sel_hi:[1,0,1]
	s_waitcnt lgkmcnt(3)
	v_pk_fma_f32 v[48:49], v[120:121], v[46:47], v[18:19] op_sel_hi:[1,0,1]
	s_waitcnt lgkmcnt(2)
	v_pk_fma_f32 v[50:51], v[120:121], v[40:41], v[20:21] op_sel_hi:[1,0,1]
	s_waitcnt lgkmcnt(1)
	v_pk_fma_f32 v[30:31], v[120:121], v[52:53], v[30:31] op_sel_hi:[1,0,1]
	s_waitcnt lgkmcnt(0)
	v_pk_fma_f32 v[32:33], v[120:121], v[42:43], v[32:33] op_sel_hi:[1,0,1]
	v_pk_fma_f32 v[6:7], v[122:123], v[44:45], v[6:7] op_sel_hi:[1,0,1]
	v_pk_fma_f32 v[8:9], v[122:123], v[46:47], v[8:9] op_sel_hi:[1,0,1]
	v_pk_fma_f32 v[10:11], v[122:123], v[40:41], v[10:11] op_sel_hi:[1,0,1]
	v_pk_fma_f32 v[54:55], v[122:123], v[52:53], v[12:13] op_sel_hi:[1,0,1]
	v_pk_fma_f32 v[56:57], v[122:123], v[42:43], v[14:15] op_sel_hi:[1,0,1]
	v_mov_b32_e32 v12, v45
	s_waitcnt vmcnt(0)
	v_pk_fma_f32 v[20:21], v[126:127], v[12:13], v[6:7] op_sel_hi:[1,0,1]
	v_mov_b32_e32 v6, v47
	v_pk_fma_f32 v[18:19], v[124:125], v[12:13], v[16:17] op_sel_hi:[1,0,1]
	v_pk_fma_f32 v[16:17], v[126:127], v[6:7], v[8:9] op_sel_hi:[1,0,1]
	v_pk_fma_f32 v[14:15], v[124:125], v[6:7], v[48:49] op_sel_hi:[1,0,1]
	v_mov_b32_e32 v6, v41
	v_pk_fma_f32 v[12:13], v[126:127], v[6:7], v[10:11] op_sel_hi:[1,0,1]
	v_pk_fma_f32 v[10:11], v[124:125], v[6:7], v[50:51] op_sel_hi:[1,0,1]
	v_mov_b32_e32 v6, v53
	v_pk_fma_f32 v[8:9], v[126:127], v[6:7], v[54:55] op_sel_hi:[1,0,1]
	v_pk_fma_f32 v[6:7], v[124:125], v[6:7], v[30:31] op_sel_hi:[1,0,1]
	v_mov_b32_e32 v30, v43
	v_pk_fma_f32 v[4:5], v[126:127], v[30:31], v[56:57] op_sel_hi:[1,0,1]
	v_pk_fma_f32 v[2:3], v[124:125], v[30:31], v[32:33] op_sel_hi:[1,0,1]
	s_cbranch_scc1 .LBB0_29
	ds_write_b128 v37, v[18:21] offset:32768
	ds_write_b128 v37, v[14:17] offset:33280
	ds_write_b128 v37, v[10:13] offset:33792
	ds_write_b128 v37, v[6:9] offset:34304
	ds_write_b128 v37, v[2:5] offset:34816
	s_waitcnt lgkmcnt(0)
	s_barrier
	s_and_saveexec_b64 s[8:9], vcc
	s_cbranch_execz .LBB0_27
	s_load_dwordx2 s[12:13], s[0:1], 0x28
	s_mul_i32 s14, s11, 0x1800
	s_add_i32 s14, s14, s6
	v_or_b32_e32 v2, s14, v25
	v_ashrrev_i32_e32 v3, 31, v2
	s_mul_i32 s11, s11, 5
	s_waitcnt lgkmcnt(0)
	v_lshl_add_u64 v[2:3], v[2:3], 2, s[12:13]
	v_lshl_add_u64 v[4:5], s[6:7], 2, v[26:27]
	s_mov_b64 s[6:7], 0
	v_mov_b32_e32 v6, v170
